# v115 + P5 merge-GEMM epilogue: the four gate chunks of each 16-row pair loaded together (counted waits) instead of one at a time behind vmcnt(0)
# baseline (speedup 1.0000x reference)
.LBB0_845:
	v_mov_b32_e32 v142, v165
	v_mov_b32_e32 v143, v150
	v_mov_b32_e32 v144, v1
	v_mov_b32_e32 v145, v151
	s_lshl_b32 s4, s33, 8
	s_lshl_b32 s2, s2, 8
	s_add_i32 s4, s4, s30
	v_add_u32_e32 v144, s4, v143
	s_or_b32 s2, s2, s31
	v_lshl_add_u32 v142, v145, 3, s2
	v_ashrrev_i32_e32 v145, 31, v144
	v_lshlrev_b64 v[146:147], 13, v[144:145]
	v_lshl_add_u64 v[146:147], s[70:71], 0, v[146:147]
	v_ashrrev_i32_e32 v143, 31, v142
	v_lshl_add_u64 v[146:147], v[142:143], 1, v[146:147]
	v_lshl_add_u64 v[188:189], v[146:147], 0, s[12:13]
	global_load_dwordx4 v[172:175], v[188:189], off
	global_load_dwordx4 v[176:179], v[146:147], off
	global_load_dwordx4 v[180:183], v[188:189], off offset:256
	global_load_dwordx4 v[184:187], v[146:147], off offset:256
	v_add_co_u32_e32 v148, vcc, s38, v146
	s_cmp_lg_u32 s44, 3
	s_nop 0
	v_addc_co_u32_e32 v149, vcc, 0, v147, vcc
	v_lshlrev_b64 v[148:149], 12, v[144:145]
	s_cselect_b64 s[20:21], -1, 0
	v_lshl_add_u64 v[148:149], s[82:83], 0, v[148:149]
	s_mov_b64 s[4:5], -1
	s_and_b64 vcc, exec, s[20:21]
	v_lshl_add_u64 v[148:149], v[142:143], 1, v[148:149]
	s_waitcnt vmcnt(3)
	v_lshlrev_b32_e32 v159, 16, v172
	v_and_b32_e32 v158, 0xffff0000, v172
	v_lshlrev_b32_e32 v155, 16, v173
	v_and_b32_e32 v154, 0xffff0000, v173
	v_lshlrev_b32_e32 v160, 16, v174
	v_and_b32_e32 v157, 0xffff0000, v174
	v_lshlrev_b32_e32 v156, 16, v175
	v_and_b32_e32 v145, 0xffff0000, v175
	s_cbranch_vccz .LBB0_847
	v_mul_f32_e32 v161, v126, v159
	v_mul_f32_e32 v162, v127, v158
	v_cvt_pk_bf16_f32 v166, v161, v162
	v_mul_f32_e32 v161, v128, v155
	v_mul_f32_e32 v162, v129, v154
	v_cvt_pk_bf16_f32 v167, v161, v162
	v_mul_f32_e32 v161, v122, v160
	v_mul_f32_e32 v162, v123, v157
	v_cvt_pk_bf16_f32 v168, v161, v162
	v_mul_f32_e32 v161, v124, v156
	v_mul_f32_e32 v162, v125, v145
	v_cvt_pk_bf16_f32 v169, v161, v162
	global_store_dwordx4 v[148:149], v[166:169], off
	s_mov_b64 s[4:5], 0
.LBB0_847:
	s_andn2_b64 vcc, exec, s[4:5]
	s_cbranch_vccnz .LBB0_849
	v_max_f32_e32 v159, v159, v159
	v_max_f32_e32 v160, v160, v160
	v_max_f32_e32 v158, v158, v158
	v_max_f32_e32 v157, v157, v157
	v_max_f32_e32 v155, v155, v155
	v_max_f32_e32 v156, v156, v156
	v_max_f32_e32 v154, v154, v154
	v_max_f32_e32 v145, v145, v145
	v_max_f32_e32 v159, 0xda24260, v159
	v_max_f32_e32 v160, 0xda24260, v160
	v_max_f32_e32 v158, 0xda24260, v158
	v_max_f32_e32 v157, 0xda24260, v157
	v_max_f32_e32 v161, 0xda24260, v155
	v_max_f32_e32 v162, 0xda24260, v156
	v_max_f32_e32 v163, 0xda24260, v154
	v_max_f32_e32 v145, 0xda24260, v145
	v_rcp_f32_e32 v154, v159
	v_rcp_f32_e32 v156, v160
	v_rcp_f32_e32 v155, v158
	v_rcp_f32_e32 v157, v157
	v_rcp_f32_e32 v158, v161
	v_rcp_f32_e32 v160, v162
	v_rcp_f32_e32 v159, v163
	v_rcp_f32_e32 v161, v145
	s_waitcnt vmcnt(2)
	v_lshlrev_b32_e32 v162, 16, v176
	v_and_b32_e32 v163, 0xffff0000, v176
	v_lshlrev_b32_e32 v170, 16, v178
	v_and_b32_e32 v171, 0xffff0000, v178
	v_lshlrev_b32_e32 v166, 16, v177
	v_and_b32_e32 v167, 0xffff0000, v177
	v_lshlrev_b32_e32 v168, 16, v179
	v_and_b32_e32 v169, 0xffff0000, v179
	v_pk_mul_f32 v[154:155], v[154:155], v[162:163]
	v_pk_mul_f32 v[156:157], v[156:157], v[170:171]
	v_pk_mul_f32 v[158:159], v[158:159], v[166:167]
	v_pk_mul_f32 v[160:161], v[160:161], v[168:169]
	v_pk_mul_f32 v[126:127], v[126:127], v[154:155]
	v_pk_mul_f32 v[122:123], v[122:123], v[156:157]
	v_pk_mul_f32 v[128:129], v[128:129], v[158:159]
	v_pk_mul_f32 v[124:125], v[124:125], v[160:161]
.LBB0_849:
	v_lshl_add_u64 v[154:155], v[146:147], 0, s[12:13]
	v_cndmask_b32_e64 v145, 0, 1, s[20:21]
	v_cmp_ne_u32_e64 s[4:5], 1, v145
	s_andn2_b64 vcc, exec, s[20:21]
	s_mov_b64 s[20:21], -1
	s_waitcnt vmcnt(1)
	v_lshlrev_b32_e32 v159, 16, v180
	v_and_b32_e32 v158, 0xffff0000, v180
	v_lshlrev_b32_e32 v155, 16, v181
	v_and_b32_e32 v154, 0xffff0000, v181
	v_lshlrev_b32_e32 v160, 16, v182
	v_and_b32_e32 v157, 0xffff0000, v182
	v_lshlrev_b32_e32 v156, 16, v183
	v_and_b32_e32 v145, 0xffff0000, v183
	s_cbranch_vccnz .LBB0_851
	v_mul_f32_e32 v161, v94, v159
	v_mul_f32_e32 v162, v95, v158
	v_cvt_pk_bf16_f32 v166, v161, v162
	v_mul_f32_e32 v161, v96, v155
	v_mul_f32_e32 v162, v97, v154
	v_cvt_pk_bf16_f32 v167, v161, v162
	v_mul_f32_e32 v161, v90, v160
	v_mul_f32_e32 v162, v91, v157
	s_mov_b64 s[20:21], 0
	v_cvt_pk_bf16_f32 v168, v161, v162
	v_mul_f32_e32 v161, v92, v156
	v_mul_f32_e32 v162, v93, v145
	v_cvt_pk_bf16_f32 v169, v161, v162
	global_store_dwordx4 v[148:149], v[166:169], off offset:256
.LBB0_851:
	s_andn2_b64 vcc, exec, s[20:21]
	s_cbranch_vccnz .LBB0_853
	v_max_f32_e32 v159, v159, v159
	v_max_f32_e32 v160, v160, v160
	v_max_f32_e32 v158, v158, v158
	v_max_f32_e32 v157, v157, v157
	v_max_f32_e32 v155, v155, v155
	v_max_f32_e32 v156, v156, v156
	v_max_f32_e32 v154, v154, v154
	v_max_f32_e32 v145, v145, v145
	v_max_f32_e32 v159, 0xda24260, v159
	v_max_f32_e32 v160, 0xda24260, v160
	v_max_f32_e32 v158, 0xda24260, v158
	v_max_f32_e32 v157, 0xda24260, v157
	v_max_f32_e32 v161, 0xda24260, v155
	v_max_f32_e32 v162, 0xda24260, v156
	v_max_f32_e32 v163, 0xda24260, v154
	v_max_f32_e32 v145, 0xda24260, v145
	v_rcp_f32_e32 v154, v159
	v_rcp_f32_e32 v156, v160
	v_rcp_f32_e32 v155, v158
	v_rcp_f32_e32 v157, v157
	v_rcp_f32_e32 v158, v161
	v_rcp_f32_e32 v160, v162
	v_rcp_f32_e32 v159, v163
	v_rcp_f32_e32 v161, v145
	s_waitcnt vmcnt(0)
	v_lshlrev_b32_e32 v162, 16, v184
	v_and_b32_e32 v163, 0xffff0000, v184
	v_lshlrev_b32_e32 v166, 16, v186
	v_and_b32_e32 v167, 0xffff0000, v186
	v_lshlrev_b32_e32 v146, 16, v185
	v_and_b32_e32 v147, 0xffff0000, v185
	v_lshlrev_b32_e32 v148, 16, v187
	v_and_b32_e32 v149, 0xffff0000, v187
	v_pk_mul_f32 v[154:155], v[154:155], v[162:163]
	v_pk_mul_f32 v[156:157], v[156:157], v[166:167]
	v_pk_mul_f32 v[146:147], v[158:159], v[146:147]
	v_pk_mul_f32 v[148:149], v[160:161], v[148:149]
	v_pk_mul_f32 v[94:95], v[94:95], v[154:155]
	v_pk_mul_f32 v[90:91], v[90:91], v[156:157]
	v_pk_mul_f32 v[96:97], v[96:97], v[146:147]
	v_pk_mul_f32 v[92:93], v[92:93], v[148:149]
.LBB0_853:
	v_add_u32_e32 v148, 16, v144
	v_ashrrev_i32_e32 v149, 31, v148
	v_lshlrev_b64 v[146:147], 13, v[148:149]
	v_lshl_add_u64 v[146:147], s[70:71], 0, v[146:147]
	v_lshl_add_u64 v[146:147], v[142:143], 1, v[146:147]
	v_lshl_add_u64 v[188:189], v[146:147], 0, s[12:13]
	global_load_dwordx4 v[172:175], v[188:189], off
	global_load_dwordx4 v[176:179], v[146:147], off
	global_load_dwordx4 v[180:183], v[188:189], off offset:256
	global_load_dwordx4 v[184:187], v[146:147], off offset:256
	v_add_co_u32_e32 v154, vcc, 0x1000, v146
	v_lshlrev_b64 v[148:149], 12, v[148:149]
	s_nop 0
	v_addc_co_u32_e32 v155, vcc, 0, v147, vcc
	v_lshl_add_u64 v[148:149], s[82:83], 0, v[148:149]
	s_mov_b64 s[20:21], -1
	s_and_b64 vcc, exec, s[4:5]
	v_lshl_add_u64 v[148:149], v[142:143], 1, v[148:149]
	s_waitcnt vmcnt(3)
	v_lshlrev_b32_e32 v159, 16, v172
	v_and_b32_e32 v158, 0xffff0000, v172
	v_lshlrev_b32_e32 v155, 16, v173
	v_and_b32_e32 v154, 0xffff0000, v173
	v_lshlrev_b32_e32 v160, 16, v174
	v_and_b32_e32 v157, 0xffff0000, v174
	v_lshlrev_b32_e32 v156, 16, v175
	v_and_b32_e32 v145, 0xffff0000, v175
	s_cbranch_vccnz .LBB0_855
	v_mul_f32_e32 v161, v118, v159
	v_mul_f32_e32 v162, v119, v158
	v_cvt_pk_bf16_f32 v166, v161, v162
	v_mul_f32_e32 v161, v120, v155
	v_mul_f32_e32 v162, v121, v154
	v_cvt_pk_bf16_f32 v167, v161, v162
	v_mul_f32_e32 v161, v114, v160
	v_mul_f32_e32 v162, v115, v157
	s_mov_b64 s[20:21], 0
	v_cvt_pk_bf16_f32 v168, v161, v162
	v_mul_f32_e32 v161, v116, v156
	v_mul_f32_e32 v162, v117, v145
	v_cvt_pk_bf16_f32 v169, v161, v162
	global_store_dwordx4 v[148:149], v[166:169], off
.LBB0_855:
	s_andn2_b64 vcc, exec, s[20:21]
	s_cbranch_vccnz .LBB0_857
	v_max_f32_e32 v159, v159, v159
	v_max_f32_e32 v160, v160, v160
	v_max_f32_e32 v158, v158, v158
	v_max_f32_e32 v157, v157, v157
	v_max_f32_e32 v155, v155, v155
	v_max_f32_e32 v156, v156, v156
	v_max_f32_e32 v154, v154, v154
	v_max_f32_e32 v145, v145, v145
	v_max_f32_e32 v159, 0xda24260, v159
	v_max_f32_e32 v160, 0xda24260, v160
	v_max_f32_e32 v158, 0xda24260, v158
	v_max_f32_e32 v157, 0xda24260, v157
	v_max_f32_e32 v161, 0xda24260, v155
	v_max_f32_e32 v162, 0xda24260, v156
	v_max_f32_e32 v163, 0xda24260, v154
	v_max_f32_e32 v145, 0xda24260, v145
	v_rcp_f32_e32 v154, v159
	v_rcp_f32_e32 v156, v160
	v_rcp_f32_e32 v155, v158
	v_rcp_f32_e32 v157, v157
	v_rcp_f32_e32 v158, v161
	v_rcp_f32_e32 v160, v162
	v_rcp_f32_e32 v159, v163
	v_rcp_f32_e32 v161, v145
	s_waitcnt vmcnt(2)
	v_lshlrev_b32_e32 v162, 16, v176
	v_and_b32_e32 v163, 0xffff0000, v176
	v_lshlrev_b32_e32 v170, 16, v178
	v_and_b32_e32 v171, 0xffff0000, v178
	v_lshlrev_b32_e32 v166, 16, v177
	v_and_b32_e32 v167, 0xffff0000, v177
	v_lshlrev_b32_e32 v168, 16, v179
	v_and_b32_e32 v169, 0xffff0000, v179
	v_pk_mul_f32 v[154:155], v[154:155], v[162:163]
	v_pk_mul_f32 v[156:157], v[156:157], v[170:171]
	v_pk_mul_f32 v[158:159], v[158:159], v[166:167]
	v_pk_mul_f32 v[160:161], v[160:161], v[168:169]
	v_pk_mul_f32 v[118:119], v[118:119], v[154:155]
	v_pk_mul_f32 v[114:115], v[114:115], v[156:157]
	v_pk_mul_f32 v[120:121], v[120:121], v[158:159]
	v_pk_mul_f32 v[116:117], v[116:117], v[160:161]
.LBB0_857:
	v_lshl_add_u64 v[154:155], v[146:147], 0, s[12:13]
	s_and_b64 vcc, exec, s[4:5]
	s_mov_b64 s[20:21], -1
	s_waitcnt vmcnt(1)
	v_lshlrev_b32_e32 v159, 16, v180
	v_and_b32_e32 v158, 0xffff0000, v180
	v_lshlrev_b32_e32 v155, 16, v181
	v_and_b32_e32 v154, 0xffff0000, v181
	v_lshlrev_b32_e32 v160, 16, v182
	v_and_b32_e32 v157, 0xffff0000, v182
	v_lshlrev_b32_e32 v156, 16, v183
	v_and_b32_e32 v145, 0xffff0000, v183
	s_cbranch_vccnz .LBB0_859
	v_mul_f32_e32 v161, v86, v159
	v_mul_f32_e32 v162, v87, v158
	v_cvt_pk_bf16_f32 v166, v161, v162
	v_mul_f32_e32 v161, v88, v155
	v_mul_f32_e32 v162, v89, v154
	v_cvt_pk_bf16_f32 v167, v161, v162
	v_mul_f32_e32 v161, v82, v160
	v_mul_f32_e32 v162, v83, v157
	s_mov_b64 s[20:21], 0
	v_cvt_pk_bf16_f32 v168, v161, v162
	v_mul_f32_e32 v161, v84, v156
	v_mul_f32_e32 v162, v85, v145
	v_cvt_pk_bf16_f32 v169, v161, v162
	global_store_dwordx4 v[148:149], v[166:169], off offset:256
.LBB0_859:
	s_andn2_b64 vcc, exec, s[20:21]
	s_cbranch_vccnz .LBB0_861
	v_max_f32_e32 v159, v159, v159
	v_max_f32_e32 v160, v160, v160
	v_max_f32_e32 v158, v158, v158
	v_max_f32_e32 v157, v157, v157
	v_max_f32_e32 v155, v155, v155
	v_max_f32_e32 v156, v156, v156
	v_max_f32_e32 v154, v154, v154
	v_max_f32_e32 v145, v145, v145
	v_max_f32_e32 v159, 0xda24260, v159
	v_max_f32_e32 v160, 0xda24260, v160
	v_max_f32_e32 v158, 0xda24260, v158
	v_max_f32_e32 v157, 0xda24260, v157
	v_max_f32_e32 v161, 0xda24260, v155
	v_max_f32_e32 v162, 0xda24260, v156
	v_max_f32_e32 v163, 0xda24260, v154
	v_max_f32_e32 v145, 0xda24260, v145
	v_rcp_f32_e32 v154, v159
	v_rcp_f32_e32 v156, v160
	v_rcp_f32_e32 v155, v158
	v_rcp_f32_e32 v157, v157
	v_rcp_f32_e32 v158, v161
	v_rcp_f32_e32 v160, v162
	v_rcp_f32_e32 v159, v163
	v_rcp_f32_e32 v161, v145
	s_waitcnt vmcnt(0)
	v_lshlrev_b32_e32 v162, 16, v184
	v_and_b32_e32 v163, 0xffff0000, v184
	v_lshlrev_b32_e32 v166, 16, v186
	v_and_b32_e32 v167, 0xffff0000, v186
	v_lshlrev_b32_e32 v146, 16, v185
	v_and_b32_e32 v147, 0xffff0000, v185
	v_lshlrev_b32_e32 v148, 16, v187
	v_and_b32_e32 v149, 0xffff0000, v187
	v_pk_mul_f32 v[154:155], v[154:155], v[162:163]
	v_pk_mul_f32 v[156:157], v[156:157], v[166:167]
	v_pk_mul_f32 v[146:147], v[158:159], v[146:147]
	v_pk_mul_f32 v[148:149], v[160:161], v[148:149]
	v_pk_mul_f32 v[86:87], v[86:87], v[154:155]
	v_pk_mul_f32 v[82:83], v[82:83], v[156:157]
	v_pk_mul_f32 v[88:89], v[88:89], v[146:147]
	v_pk_mul_f32 v[84:85], v[84:85], v[148:149]
.LBB0_861:
	v_add_u32_e32 v148, 32, v144
	v_ashrrev_i32_e32 v149, 31, v148
	v_lshlrev_b64 v[146:147], 13, v[148:149]
	v_lshl_add_u64 v[146:147], s[70:71], 0, v[146:147]
	v_lshl_add_u64 v[146:147], v[142:143], 1, v[146:147]
	v_lshl_add_u64 v[188:189], v[146:147], 0, s[12:13]
	global_load_dwordx4 v[172:175], v[188:189], off
	global_load_dwordx4 v[176:179], v[146:147], off
	global_load_dwordx4 v[180:183], v[188:189], off offset:256
	global_load_dwordx4 v[184:187], v[146:147], off offset:256
	v_add_co_u32_e32 v154, vcc, 0x1000, v146
	v_lshlrev_b64 v[148:149], 12, v[148:149]
	s_nop 0
	v_addc_co_u32_e32 v155, vcc, 0, v147, vcc
	v_lshl_add_u64 v[148:149], s[82:83], 0, v[148:149]
	s_mov_b64 s[20:21], -1
	s_and_b64 vcc, exec, s[4:5]
	v_lshl_add_u64 v[148:149], v[142:143], 1, v[148:149]
	s_waitcnt vmcnt(3)
	v_lshlrev_b32_e32 v159, 16, v172
	v_and_b32_e32 v158, 0xffff0000, v172
	v_lshlrev_b32_e32 v155, 16, v173
	v_and_b32_e32 v154, 0xffff0000, v173
	v_lshlrev_b32_e32 v160, 16, v174
	v_and_b32_e32 v157, 0xffff0000, v174
	v_lshlrev_b32_e32 v156, 16, v175
	v_and_b32_e32 v145, 0xffff0000, v175
	s_cbranch_vccnz .LBB0_863
	v_mul_f32_e32 v161, v110, v159
	v_mul_f32_e32 v162, v111, v158
	v_cvt_pk_bf16_f32 v166, v161, v162
	v_mul_f32_e32 v161, v112, v155
	v_mul_f32_e32 v162, v113, v154
	v_cvt_pk_bf16_f32 v167, v161, v162
	v_mul_f32_e32 v161, v106, v160
	v_mul_f32_e32 v162, v107, v157
	s_mov_b64 s[20:21], 0
	v_cvt_pk_bf16_f32 v168, v161, v162
	v_mul_f32_e32 v161, v108, v156
	v_mul_f32_e32 v162, v109, v145
	v_cvt_pk_bf16_f32 v169, v161, v162
	global_store_dwordx4 v[148:149], v[166:169], off
.LBB0_863:
	s_andn2_b64 vcc, exec, s[20:21]
	s_cbranch_vccnz .LBB0_865
	v_max_f32_e32 v159, v159, v159
	v_max_f32_e32 v160, v160, v160
	v_max_f32_e32 v158, v158, v158
	v_max_f32_e32 v157, v157, v157
	v_max_f32_e32 v155, v155, v155
	v_max_f32_e32 v156, v156, v156
	v_max_f32_e32 v154, v154, v154
	v_max_f32_e32 v145, v145, v145
	v_max_f32_e32 v159, 0xda24260, v159
	v_max_f32_e32 v160, 0xda24260, v160
	v_max_f32_e32 v158, 0xda24260, v158
	v_max_f32_e32 v157, 0xda24260, v157
	v_max_f32_e32 v161, 0xda24260, v155
	v_max_f32_e32 v162, 0xda24260, v156
	v_max_f32_e32 v163, 0xda24260, v154
	v_max_f32_e32 v145, 0xda24260, v145
	v_rcp_f32_e32 v154, v159
	v_rcp_f32_e32 v156, v160
	v_rcp_f32_e32 v155, v158
	v_rcp_f32_e32 v157, v157
	v_rcp_f32_e32 v158, v161
	v_rcp_f32_e32 v160, v162
	v_rcp_f32_e32 v159, v163
	v_rcp_f32_e32 v161, v145
	s_waitcnt vmcnt(2)
	v_lshlrev_b32_e32 v162, 16, v176
	v_and_b32_e32 v163, 0xffff0000, v176
	v_lshlrev_b32_e32 v170, 16, v178
	v_and_b32_e32 v171, 0xffff0000, v178
	v_lshlrev_b32_e32 v166, 16, v177
	v_and_b32_e32 v167, 0xffff0000, v177
	v_lshlrev_b32_e32 v168, 16, v179
	v_and_b32_e32 v169, 0xffff0000, v179
	v_pk_mul_f32 v[154:155], v[154:155], v[162:163]
	v_pk_mul_f32 v[156:157], v[156:157], v[170:171]
	v_pk_mul_f32 v[158:159], v[158:159], v[166:167]
	v_pk_mul_f32 v[160:161], v[160:161], v[168:169]
	v_pk_mul_f32 v[110:111], v[110:111], v[154:155]
	v_pk_mul_f32 v[106:107], v[106:107], v[156:157]
	v_pk_mul_f32 v[112:113], v[112:113], v[158:159]
	v_pk_mul_f32 v[108:109], v[108:109], v[160:161]
.LBB0_865:
	v_lshl_add_u64 v[154:155], v[146:147], 0, s[12:13]
	s_and_b64 vcc, exec, s[4:5]
	s_mov_b64 s[20:21], -1
	s_waitcnt vmcnt(1)
	v_lshlrev_b32_e32 v159, 16, v180
	v_and_b32_e32 v158, 0xffff0000, v180
	v_lshlrev_b32_e32 v155, 16, v181
	v_and_b32_e32 v154, 0xffff0000, v181
	v_lshlrev_b32_e32 v160, 16, v182
	v_and_b32_e32 v157, 0xffff0000, v182
	v_lshlrev_b32_e32 v156, 16, v183
	v_and_b32_e32 v145, 0xffff0000, v183
	s_cbranch_vccnz .LBB0_867
	v_mul_f32_e32 v161, v78, v159
	v_mul_f32_e32 v162, v79, v158
	v_cvt_pk_bf16_f32 v166, v161, v162
	v_mul_f32_e32 v161, v80, v155
	v_mul_f32_e32 v162, v81, v154
	v_cvt_pk_bf16_f32 v167, v161, v162
	v_mul_f32_e32 v161, v74, v160
	v_mul_f32_e32 v162, v75, v157
	s_mov_b64 s[20:21], 0
	v_cvt_pk_bf16_f32 v168, v161, v162
	v_mul_f32_e32 v161, v76, v156
	v_mul_f32_e32 v162, v77, v145
	v_cvt_pk_bf16_f32 v169, v161, v162
	global_store_dwordx4 v[148:149], v[166:169], off offset:256
.LBB0_867:
	s_andn2_b64 vcc, exec, s[20:21]
	s_cbranch_vccnz .LBB0_869
	v_max_f32_e32 v159, v159, v159
	v_max_f32_e32 v160, v160, v160
	v_max_f32_e32 v158, v158, v158
	v_max_f32_e32 v157, v157, v157
	v_max_f32_e32 v155, v155, v155
	v_max_f32_e32 v156, v156, v156
	v_max_f32_e32 v154, v154, v154
	v_max_f32_e32 v145, v145, v145
	v_max_f32_e32 v159, 0xda24260, v159
	v_max_f32_e32 v160, 0xda24260, v160
	v_max_f32_e32 v158, 0xda24260, v158
	v_max_f32_e32 v157, 0xda24260, v157
	v_max_f32_e32 v161, 0xda24260, v155
	v_max_f32_e32 v162, 0xda24260, v156
	v_max_f32_e32 v163, 0xda24260, v154
	v_max_f32_e32 v145, 0xda24260, v145
	v_rcp_f32_e32 v154, v159
	v_rcp_f32_e32 v156, v160
	v_rcp_f32_e32 v155, v158
	v_rcp_f32_e32 v157, v157
	v_rcp_f32_e32 v158, v161
	v_rcp_f32_e32 v160, v162
	v_rcp_f32_e32 v159, v163
	v_rcp_f32_e32 v161, v145
	s_waitcnt vmcnt(0)
	v_lshlrev_b32_e32 v162, 16, v184
	v_and_b32_e32 v163, 0xffff0000, v184
	v_lshlrev_b32_e32 v166, 16, v186
	v_and_b32_e32 v167, 0xffff0000, v186
	v_lshlrev_b32_e32 v146, 16, v185
	v_and_b32_e32 v147, 0xffff0000, v185
	v_lshlrev_b32_e32 v148, 16, v187
	v_and_b32_e32 v149, 0xffff0000, v187
	v_pk_mul_f32 v[154:155], v[154:155], v[162:163]
	v_pk_mul_f32 v[156:157], v[156:157], v[166:167]
	v_pk_mul_f32 v[146:147], v[158:159], v[146:147]
	v_pk_mul_f32 v[148:149], v[160:161], v[148:149]
	v_pk_mul_f32 v[78:79], v[78:79], v[154:155]
	v_pk_mul_f32 v[74:75], v[74:75], v[156:157]
	v_pk_mul_f32 v[80:81], v[80:81], v[146:147]
	v_pk_mul_f32 v[76:77], v[76:77], v[148:149]
.LBB0_869:
	v_add_u32_e32 v148, 48, v144
	v_ashrrev_i32_e32 v149, 31, v148
	v_lshlrev_b64 v[146:147], 13, v[148:149]
	v_lshl_add_u64 v[146:147], s[70:71], 0, v[146:147]
	v_lshl_add_u64 v[146:147], v[142:143], 1, v[146:147]
	v_lshl_add_u64 v[188:189], v[146:147], 0, s[12:13]
	global_load_dwordx4 v[172:175], v[188:189], off
	global_load_dwordx4 v[176:179], v[146:147], off
	global_load_dwordx4 v[180:183], v[188:189], off offset:256
	global_load_dwordx4 v[184:187], v[146:147], off offset:256
	v_add_co_u32_e32 v154, vcc, 0x1000, v146
	v_lshlrev_b64 v[148:149], 12, v[148:149]
	s_nop 0
	v_addc_co_u32_e32 v155, vcc, 0, v147, vcc
	v_lshl_add_u64 v[148:149], s[82:83], 0, v[148:149]
	s_mov_b64 s[20:21], -1
	s_and_b64 vcc, exec, s[4:5]
	v_lshl_add_u64 v[148:149], v[142:143], 1, v[148:149]
	s_waitcnt vmcnt(3)
	v_lshlrev_b32_e32 v159, 16, v172
	v_and_b32_e32 v158, 0xffff0000, v172
	v_lshlrev_b32_e32 v155, 16, v173
	v_and_b32_e32 v154, 0xffff0000, v173
	v_lshlrev_b32_e32 v160, 16, v174
	v_and_b32_e32 v157, 0xffff0000, v174
	v_lshlrev_b32_e32 v156, 16, v175
	v_and_b32_e32 v145, 0xffff0000, v175
	s_cbranch_vccnz .LBB0_871
	v_mul_f32_e32 v161, v102, v159
	v_mul_f32_e32 v162, v103, v158
	v_cvt_pk_bf16_f32 v166, v161, v162
	v_mul_f32_e32 v161, v104, v155
	v_mul_f32_e32 v162, v105, v154
	v_cvt_pk_bf16_f32 v167, v161, v162
	v_mul_f32_e32 v161, v98, v160
	v_mul_f32_e32 v162, v99, v157
	s_mov_b64 s[20:21], 0
	v_cvt_pk_bf16_f32 v168, v161, v162
	v_mul_f32_e32 v161, v100, v156
	v_mul_f32_e32 v162, v101, v145
	v_cvt_pk_bf16_f32 v169, v161, v162
	global_store_dwordx4 v[148:149], v[166:169], off
.LBB0_871:
	s_andn2_b64 vcc, exec, s[20:21]
	s_cbranch_vccnz .LBB0_873
	v_max_f32_e32 v159, v159, v159
	v_max_f32_e32 v160, v160, v160
	v_max_f32_e32 v158, v158, v158
	v_max_f32_e32 v157, v157, v157
	v_max_f32_e32 v155, v155, v155
	v_max_f32_e32 v156, v156, v156
	v_max_f32_e32 v154, v154, v154
	v_max_f32_e32 v145, v145, v145
	v_max_f32_e32 v159, 0xda24260, v159
	v_max_f32_e32 v160, 0xda24260, v160
	v_max_f32_e32 v158, 0xda24260, v158
	v_max_f32_e32 v157, 0xda24260, v157
	v_max_f32_e32 v161, 0xda24260, v155
	v_max_f32_e32 v162, 0xda24260, v156
	v_max_f32_e32 v163, 0xda24260, v154
	v_max_f32_e32 v145, 0xda24260, v145
	v_rcp_f32_e32 v154, v159
	v_rcp_f32_e32 v156, v160
	v_rcp_f32_e32 v155, v158
	v_rcp_f32_e32 v157, v157
	v_rcp_f32_e32 v158, v161
	v_rcp_f32_e32 v160, v162
	v_rcp_f32_e32 v159, v163
	v_rcp_f32_e32 v161, v145
	s_waitcnt vmcnt(2)
	v_lshlrev_b32_e32 v162, 16, v176
	v_and_b32_e32 v163, 0xffff0000, v176
	v_lshlrev_b32_e32 v170, 16, v178
	v_and_b32_e32 v171, 0xffff0000, v178
	v_lshlrev_b32_e32 v166, 16, v177
	v_and_b32_e32 v167, 0xffff0000, v177
	v_lshlrev_b32_e32 v168, 16, v179
	v_and_b32_e32 v169, 0xffff0000, v179
	v_pk_mul_f32 v[154:155], v[154:155], v[162:163]
	v_pk_mul_f32 v[156:157], v[156:157], v[170:171]
	v_pk_mul_f32 v[158:159], v[158:159], v[166:167]
	v_pk_mul_f32 v[160:161], v[160:161], v[168:169]
	v_pk_mul_f32 v[102:103], v[102:103], v[154:155]
	v_pk_mul_f32 v[98:99], v[98:99], v[156:157]
	v_pk_mul_f32 v[104:105], v[104:105], v[158:159]
	v_pk_mul_f32 v[100:101], v[100:101], v[160:161]
.LBB0_873:
	v_lshl_add_u64 v[154:155], v[146:147], 0, s[12:13]
	s_and_b64 vcc, exec, s[4:5]
	s_mov_b64 s[20:21], -1
	s_waitcnt vmcnt(1)
	v_lshlrev_b32_e32 v159, 16, v180
	v_and_b32_e32 v158, 0xffff0000, v180
	v_lshlrev_b32_e32 v155, 16, v181
	v_and_b32_e32 v154, 0xffff0000, v181
	v_lshlrev_b32_e32 v160, 16, v182
	v_and_b32_e32 v157, 0xffff0000, v182
	v_lshlrev_b32_e32 v156, 16, v183
	v_and_b32_e32 v145, 0xffff0000, v183
	s_cbranch_vccnz .LBB0_875
	v_mul_f32_e32 v161, v70, v159
	v_mul_f32_e32 v162, v71, v158
	v_cvt_pk_bf16_f32 v166, v161, v162
	v_mul_f32_e32 v161, v72, v155
	v_mul_f32_e32 v162, v73, v154
	v_cvt_pk_bf16_f32 v167, v161, v162
	v_mul_f32_e32 v161, v66, v160
	v_mul_f32_e32 v162, v67, v157
	s_mov_b64 s[20:21], 0
	v_cvt_pk_bf16_f32 v168, v161, v162
	v_mul_f32_e32 v161, v68, v156
	v_mul_f32_e32 v162, v69, v145
	v_cvt_pk_bf16_f32 v169, v161, v162
	global_store_dwordx4 v[148:149], v[166:169], off offset:256
.LBB0_875:
	s_andn2_b64 vcc, exec, s[20:21]
	s_cbranch_vccnz .LBB0_877
	v_max_f32_e32 v159, v159, v159
	v_max_f32_e32 v160, v160, v160
	v_max_f32_e32 v158, v158, v158
	v_max_f32_e32 v157, v157, v157
	v_max_f32_e32 v155, v155, v155
	v_max_f32_e32 v156, v156, v156
	v_max_f32_e32 v154, v154, v154
	v_max_f32_e32 v145, v145, v145
	v_max_f32_e32 v159, 0xda24260, v159
	v_max_f32_e32 v160, 0xda24260, v160
	v_max_f32_e32 v158, 0xda24260, v158
	v_max_f32_e32 v157, 0xda24260, v157
	v_max_f32_e32 v161, 0xda24260, v155
	v_max_f32_e32 v162, 0xda24260, v156
	v_max_f32_e32 v163, 0xda24260, v154
	v_max_f32_e32 v145, 0xda24260, v145
	v_rcp_f32_e32 v154, v159
	v_rcp_f32_e32 v156, v160
	v_rcp_f32_e32 v155, v158
	v_rcp_f32_e32 v157, v157
	v_rcp_f32_e32 v158, v161
	v_rcp_f32_e32 v160, v162
	v_rcp_f32_e32 v159, v163
	v_rcp_f32_e32 v161, v145
	s_waitcnt vmcnt(0)
	v_lshlrev_b32_e32 v162, 16, v184
	v_and_b32_e32 v163, 0xffff0000, v184
	v_lshlrev_b32_e32 v166, 16, v186
	v_and_b32_e32 v167, 0xffff0000, v186
	v_lshlrev_b32_e32 v146, 16, v185
	v_and_b32_e32 v147, 0xffff0000, v185
	v_lshlrev_b32_e32 v148, 16, v187
	v_and_b32_e32 v149, 0xffff0000, v187
	v_pk_mul_f32 v[154:155], v[154:155], v[162:163]
	v_pk_mul_f32 v[156:157], v[156:157], v[166:167]
	v_pk_mul_f32 v[146:147], v[158:159], v[146:147]
	v_pk_mul_f32 v[148:149], v[160:161], v[148:149]
	v_pk_mul_f32 v[70:71], v[70:71], v[154:155]
	v_pk_mul_f32 v[66:67], v[66:67], v[156:157]
	v_pk_mul_f32 v[72:73], v[72:73], v[146:147]
	v_pk_mul_f32 v[68:69], v[68:69], v[148:149]
.LBB0_877:
	v_add_u32_e32 v148, 0x80, v144
	v_ashrrev_i32_e32 v149, 31, v148
	v_lshlrev_b64 v[146:147], 13, v[148:149]
	v_lshl_add_u64 v[146:147], s[70:71], 0, v[146:147]
	v_lshl_add_u64 v[146:147], v[142:143], 1, v[146:147]
	v_lshl_add_u64 v[188:189], v[146:147], 0, s[12:13]
	global_load_dwordx4 v[172:175], v[188:189], off
	global_load_dwordx4 v[176:179], v[146:147], off
	global_load_dwordx4 v[180:183], v[188:189], off offset:256
	global_load_dwordx4 v[184:187], v[146:147], off offset:256
	v_add_co_u32_e32 v154, vcc, 0x1000, v146
	v_lshlrev_b64 v[148:149], 12, v[148:149]
	s_nop 0
	v_addc_co_u32_e32 v155, vcc, 0, v147, vcc
	v_lshl_add_u64 v[148:149], s[82:83], 0, v[148:149]
	s_mov_b64 s[20:21], -1
	s_and_b64 vcc, exec, s[4:5]
	v_lshl_add_u64 v[148:149], v[142:143], 1, v[148:149]
	s_waitcnt vmcnt(3)
	v_lshlrev_b32_e32 v159, 16, v172
	v_and_b32_e32 v158, 0xffff0000, v172
	v_lshlrev_b32_e32 v155, 16, v173
	v_and_b32_e32 v154, 0xffff0000, v173
	v_lshlrev_b32_e32 v160, 16, v174
	v_and_b32_e32 v157, 0xffff0000, v174
	v_lshlrev_b32_e32 v156, 16, v175
	v_and_b32_e32 v145, 0xffff0000, v175
	s_cbranch_vccnz .LBB0_879
	v_mul_f32_e32 v161, v62, v159
	v_mul_f32_e32 v162, v63, v158
	v_cvt_pk_bf16_f32 v166, v161, v162
	v_mul_f32_e32 v161, v64, v155
	v_mul_f32_e32 v162, v65, v154
	v_cvt_pk_bf16_f32 v167, v161, v162
	v_mul_f32_e32 v161, v58, v160
	v_mul_f32_e32 v162, v59, v157
	s_mov_b64 s[20:21], 0
	v_cvt_pk_bf16_f32 v168, v161, v162
	v_mul_f32_e32 v161, v60, v156
	v_mul_f32_e32 v162, v61, v145
	v_cvt_pk_bf16_f32 v169, v161, v162
	global_store_dwordx4 v[148:149], v[166:169], off
.LBB0_879:
	s_andn2_b64 vcc, exec, s[20:21]
	s_cbranch_vccnz .LBB0_881
	v_max_f32_e32 v159, v159, v159
	v_max_f32_e32 v160, v160, v160
	v_max_f32_e32 v158, v158, v158
	v_max_f32_e32 v157, v157, v157
	v_max_f32_e32 v155, v155, v155
	v_max_f32_e32 v156, v156, v156
	v_max_f32_e32 v154, v154, v154
	v_max_f32_e32 v145, v145, v145
	v_max_f32_e32 v159, 0xda24260, v159
	v_max_f32_e32 v160, 0xda24260, v160
	v_max_f32_e32 v158, 0xda24260, v158
	v_max_f32_e32 v157, 0xda24260, v157
	v_max_f32_e32 v161, 0xda24260, v155
	v_max_f32_e32 v162, 0xda24260, v156
	v_max_f32_e32 v163, 0xda24260, v154
	v_max_f32_e32 v145, 0xda24260, v145
	v_rcp_f32_e32 v154, v159
	v_rcp_f32_e32 v156, v160
	v_rcp_f32_e32 v155, v158
	v_rcp_f32_e32 v157, v157
	v_rcp_f32_e32 v158, v161
	v_rcp_f32_e32 v160, v162
	v_rcp_f32_e32 v159, v163
	v_rcp_f32_e32 v161, v145
	s_waitcnt vmcnt(2)
	v_lshlrev_b32_e32 v162, 16, v176
	v_and_b32_e32 v163, 0xffff0000, v176
	v_lshlrev_b32_e32 v170, 16, v178
	v_and_b32_e32 v171, 0xffff0000, v178
	v_lshlrev_b32_e32 v166, 16, v177
	v_and_b32_e32 v167, 0xffff0000, v177
	v_lshlrev_b32_e32 v168, 16, v179
	v_and_b32_e32 v169, 0xffff0000, v179
	v_pk_mul_f32 v[154:155], v[154:155], v[162:163]
	v_pk_mul_f32 v[156:157], v[156:157], v[170:171]
	v_pk_mul_f32 v[158:159], v[158:159], v[166:167]
	v_pk_mul_f32 v[160:161], v[160:161], v[168:169]
	v_pk_mul_f32 v[62:63], v[62:63], v[154:155]
	v_pk_mul_f32 v[58:59], v[58:59], v[156:157]
	v_pk_mul_f32 v[64:65], v[64:65], v[158:159]
	v_pk_mul_f32 v[60:61], v[60:61], v[160:161]
.LBB0_881:
	v_lshl_add_u64 v[154:155], v[146:147], 0, s[12:13]
	s_and_b64 vcc, exec, s[4:5]
	s_mov_b64 s[20:21], -1
	s_waitcnt vmcnt(1)
	v_lshlrev_b32_e32 v159, 16, v180
	v_and_b32_e32 v158, 0xffff0000, v180
	v_lshlrev_b32_e32 v155, 16, v181
	v_and_b32_e32 v154, 0xffff0000, v181
	v_lshlrev_b32_e32 v160, 16, v182
	v_and_b32_e32 v157, 0xffff0000, v182
	v_lshlrev_b32_e32 v156, 16, v183
	v_and_b32_e32 v145, 0xffff0000, v183
	s_cbranch_vccnz .LBB0_883
	v_mul_f32_e32 v161, v30, v159
	v_mul_f32_e32 v162, v31, v158
	v_cvt_pk_bf16_f32 v166, v161, v162
	v_mul_f32_e32 v161, v32, v155
	v_mul_f32_e32 v162, v33, v154
	v_cvt_pk_bf16_f32 v167, v161, v162
	v_mul_f32_e32 v161, v26, v160
	v_mul_f32_e32 v162, v27, v157
	s_mov_b64 s[20:21], 0
	v_cvt_pk_bf16_f32 v168, v161, v162
	v_mul_f32_e32 v161, v28, v156
	v_mul_f32_e32 v162, v29, v145
	v_cvt_pk_bf16_f32 v169, v161, v162
	global_store_dwordx4 v[148:149], v[166:169], off offset:256
.LBB0_883:
	s_andn2_b64 vcc, exec, s[20:21]
	s_cbranch_vccnz .LBB0_885
	v_max_f32_e32 v159, v159, v159
	v_max_f32_e32 v160, v160, v160
	v_max_f32_e32 v158, v158, v158
	v_max_f32_e32 v157, v157, v157
	v_max_f32_e32 v155, v155, v155
	v_max_f32_e32 v156, v156, v156
	v_max_f32_e32 v154, v154, v154
	v_max_f32_e32 v145, v145, v145
	v_max_f32_e32 v159, 0xda24260, v159
	v_max_f32_e32 v160, 0xda24260, v160
	v_max_f32_e32 v158, 0xda24260, v158
	v_max_f32_e32 v157, 0xda24260, v157
	v_max_f32_e32 v161, 0xda24260, v155
	v_max_f32_e32 v162, 0xda24260, v156
	v_max_f32_e32 v163, 0xda24260, v154
	v_max_f32_e32 v145, 0xda24260, v145
	v_rcp_f32_e32 v154, v159
	v_rcp_f32_e32 v156, v160
	v_rcp_f32_e32 v155, v158
	v_rcp_f32_e32 v157, v157
	v_rcp_f32_e32 v158, v161
	v_rcp_f32_e32 v160, v162
	v_rcp_f32_e32 v159, v163
	v_rcp_f32_e32 v161, v145
	s_waitcnt vmcnt(0)
	v_lshlrev_b32_e32 v162, 16, v184
	v_and_b32_e32 v163, 0xffff0000, v184
	v_lshlrev_b32_e32 v166, 16, v186
	v_and_b32_e32 v167, 0xffff0000, v186
	v_lshlrev_b32_e32 v146, 16, v185
	v_and_b32_e32 v147, 0xffff0000, v185
	v_lshlrev_b32_e32 v148, 16, v187
	v_and_b32_e32 v149, 0xffff0000, v187
	v_pk_mul_f32 v[154:155], v[154:155], v[162:163]
	v_pk_mul_f32 v[156:157], v[156:157], v[166:167]
	v_pk_mul_f32 v[146:147], v[158:159], v[146:147]
	v_pk_mul_f32 v[148:149], v[160:161], v[148:149]
	v_pk_mul_f32 v[30:31], v[30:31], v[154:155]
	v_pk_mul_f32 v[26:27], v[26:27], v[156:157]
	v_pk_mul_f32 v[32:33], v[32:33], v[146:147]
	v_pk_mul_f32 v[28:29], v[28:29], v[148:149]
.LBB0_885:
	v_add_u32_e32 v148, 0x90, v144
	v_ashrrev_i32_e32 v149, 31, v148
	v_lshlrev_b64 v[146:147], 13, v[148:149]
	v_lshl_add_u64 v[146:147], s[70:71], 0, v[146:147]
	v_lshl_add_u64 v[146:147], v[142:143], 1, v[146:147]
	v_lshl_add_u64 v[188:189], v[146:147], 0, s[12:13]
	global_load_dwordx4 v[172:175], v[188:189], off
	global_load_dwordx4 v[176:179], v[146:147], off
	global_load_dwordx4 v[180:183], v[188:189], off offset:256
	global_load_dwordx4 v[184:187], v[146:147], off offset:256
	v_add_co_u32_e32 v154, vcc, 0x1000, v146
	v_lshlrev_b64 v[148:149], 12, v[148:149]
	s_nop 0
	v_addc_co_u32_e32 v155, vcc, 0, v147, vcc
	v_lshl_add_u64 v[148:149], s[82:83], 0, v[148:149]
	s_mov_b64 s[20:21], -1
	s_and_b64 vcc, exec, s[4:5]
	v_lshl_add_u64 v[148:149], v[142:143], 1, v[148:149]
	s_waitcnt vmcnt(3)
	v_lshlrev_b32_e32 v159, 16, v172
	v_and_b32_e32 v158, 0xffff0000, v172
	v_lshlrev_b32_e32 v155, 16, v173
	v_and_b32_e32 v154, 0xffff0000, v173
	v_lshlrev_b32_e32 v160, 16, v174
	v_and_b32_e32 v157, 0xffff0000, v174
	v_lshlrev_b32_e32 v156, 16, v175
	v_and_b32_e32 v145, 0xffff0000, v175
	s_cbranch_vccnz .LBB0_887
	v_mul_f32_e32 v161, v54, v159
	v_mul_f32_e32 v162, v55, v158
	v_cvt_pk_bf16_f32 v166, v161, v162
	v_mul_f32_e32 v161, v56, v155
	v_mul_f32_e32 v162, v57, v154
	v_cvt_pk_bf16_f32 v167, v161, v162
	v_mul_f32_e32 v161, v50, v160
	v_mul_f32_e32 v162, v51, v157
	s_mov_b64 s[20:21], 0
	v_cvt_pk_bf16_f32 v168, v161, v162
	v_mul_f32_e32 v161, v52, v156
	v_mul_f32_e32 v162, v53, v145
	v_cvt_pk_bf16_f32 v169, v161, v162
	global_store_dwordx4 v[148:149], v[166:169], off
.LBB0_887:
	s_andn2_b64 vcc, exec, s[20:21]
	s_cbranch_vccnz .LBB0_889
	v_max_f32_e32 v159, v159, v159
	v_max_f32_e32 v160, v160, v160
	v_max_f32_e32 v158, v158, v158
	v_max_f32_e32 v157, v157, v157
	v_max_f32_e32 v155, v155, v155
	v_max_f32_e32 v156, v156, v156
	v_max_f32_e32 v154, v154, v154
	v_max_f32_e32 v145, v145, v145
	v_max_f32_e32 v159, 0xda24260, v159
	v_max_f32_e32 v160, 0xda24260, v160
	v_max_f32_e32 v158, 0xda24260, v158
	v_max_f32_e32 v157, 0xda24260, v157
	v_max_f32_e32 v161, 0xda24260, v155
	v_max_f32_e32 v162, 0xda24260, v156
	v_max_f32_e32 v163, 0xda24260, v154
	v_max_f32_e32 v145, 0xda24260, v145
	v_rcp_f32_e32 v154, v159
	v_rcp_f32_e32 v156, v160
	v_rcp_f32_e32 v155, v158
	v_rcp_f32_e32 v157, v157
	v_rcp_f32_e32 v158, v161
	v_rcp_f32_e32 v160, v162
	v_rcp_f32_e32 v159, v163
	v_rcp_f32_e32 v161, v145
	s_waitcnt vmcnt(2)
	v_lshlrev_b32_e32 v162, 16, v176
	v_and_b32_e32 v163, 0xffff0000, v176
	v_lshlrev_b32_e32 v170, 16, v178
	v_and_b32_e32 v171, 0xffff0000, v178
	v_lshlrev_b32_e32 v166, 16, v177
	v_and_b32_e32 v167, 0xffff0000, v177
	v_lshlrev_b32_e32 v168, 16, v179
	v_and_b32_e32 v169, 0xffff0000, v179
	v_pk_mul_f32 v[154:155], v[154:155], v[162:163]
	v_pk_mul_f32 v[156:157], v[156:157], v[170:171]
	v_pk_mul_f32 v[158:159], v[158:159], v[166:167]
	v_pk_mul_f32 v[160:161], v[160:161], v[168:169]
	v_pk_mul_f32 v[54:55], v[54:55], v[154:155]
	v_pk_mul_f32 v[50:51], v[50:51], v[156:157]
	v_pk_mul_f32 v[56:57], v[56:57], v[158:159]
	v_pk_mul_f32 v[52:53], v[52:53], v[160:161]
.LBB0_889:
	v_lshl_add_u64 v[154:155], v[146:147], 0, s[12:13]
	s_and_b64 vcc, exec, s[4:5]
	s_mov_b64 s[20:21], -1
	s_waitcnt vmcnt(1)
	v_lshlrev_b32_e32 v159, 16, v180
	v_and_b32_e32 v158, 0xffff0000, v180
	v_lshlrev_b32_e32 v155, 16, v181
	v_and_b32_e32 v154, 0xffff0000, v181
	v_lshlrev_b32_e32 v160, 16, v182
	v_and_b32_e32 v157, 0xffff0000, v182
	v_lshlrev_b32_e32 v156, 16, v183
	v_and_b32_e32 v145, 0xffff0000, v183
	s_cbranch_vccnz .LBB0_891
	v_mul_f32_e32 v161, v22, v159
	v_mul_f32_e32 v162, v23, v158
	v_cvt_pk_bf16_f32 v166, v161, v162
	v_mul_f32_e32 v161, v24, v155
	v_mul_f32_e32 v162, v25, v154
	v_cvt_pk_bf16_f32 v167, v161, v162
	v_mul_f32_e32 v161, v18, v160
	v_mul_f32_e32 v162, v19, v157
	s_mov_b64 s[20:21], 0
	v_cvt_pk_bf16_f32 v168, v161, v162
	v_mul_f32_e32 v161, v20, v156
	v_mul_f32_e32 v162, v21, v145
	v_cvt_pk_bf16_f32 v169, v161, v162
	global_store_dwordx4 v[148:149], v[166:169], off offset:256
.LBB0_891:
	s_andn2_b64 vcc, exec, s[20:21]
	s_cbranch_vccnz .LBB0_893
	v_max_f32_e32 v159, v159, v159
	v_max_f32_e32 v160, v160, v160
	v_max_f32_e32 v158, v158, v158
	v_max_f32_e32 v157, v157, v157
	v_max_f32_e32 v155, v155, v155
	v_max_f32_e32 v156, v156, v156
	v_max_f32_e32 v154, v154, v154
	v_max_f32_e32 v145, v145, v145
	v_max_f32_e32 v159, 0xda24260, v159
	v_max_f32_e32 v160, 0xda24260, v160
	v_max_f32_e32 v158, 0xda24260, v158
	v_max_f32_e32 v157, 0xda24260, v157
	v_max_f32_e32 v161, 0xda24260, v155
	v_max_f32_e32 v162, 0xda24260, v156
	v_max_f32_e32 v163, 0xda24260, v154
	v_max_f32_e32 v145, 0xda24260, v145
	v_rcp_f32_e32 v154, v159
	v_rcp_f32_e32 v156, v160
	v_rcp_f32_e32 v155, v158
	v_rcp_f32_e32 v157, v157
	v_rcp_f32_e32 v158, v161
	v_rcp_f32_e32 v160, v162
	v_rcp_f32_e32 v159, v163
	v_rcp_f32_e32 v161, v145
	s_waitcnt vmcnt(0)
	v_lshlrev_b32_e32 v162, 16, v184
	v_and_b32_e32 v163, 0xffff0000, v184
	v_lshlrev_b32_e32 v166, 16, v186
	v_and_b32_e32 v167, 0xffff0000, v186
	v_lshlrev_b32_e32 v146, 16, v185
	v_and_b32_e32 v147, 0xffff0000, v185
	v_lshlrev_b32_e32 v148, 16, v187
	v_and_b32_e32 v149, 0xffff0000, v187
	v_pk_mul_f32 v[154:155], v[154:155], v[162:163]
	v_pk_mul_f32 v[156:157], v[156:157], v[166:167]
	v_pk_mul_f32 v[146:147], v[158:159], v[146:147]
	v_pk_mul_f32 v[148:149], v[160:161], v[148:149]
	v_pk_mul_f32 v[22:23], v[22:23], v[154:155]
	v_pk_mul_f32 v[18:19], v[18:19], v[156:157]
	v_pk_mul_f32 v[24:25], v[24:25], v[146:147]
	v_pk_mul_f32 v[20:21], v[20:21], v[148:149]
.LBB0_893:
	v_add_u32_e32 v148, 0xa0, v144
	v_ashrrev_i32_e32 v149, 31, v148
	v_lshlrev_b64 v[146:147], 13, v[148:149]
	v_lshl_add_u64 v[146:147], s[70:71], 0, v[146:147]
	v_lshl_add_u64 v[146:147], v[142:143], 1, v[146:147]
	v_lshl_add_u64 v[188:189], v[146:147], 0, s[12:13]
	global_load_dwordx4 v[172:175], v[188:189], off
	global_load_dwordx4 v[176:179], v[146:147], off
	global_load_dwordx4 v[180:183], v[188:189], off offset:256
	global_load_dwordx4 v[184:187], v[146:147], off offset:256
	v_add_co_u32_e32 v154, vcc, 0x1000, v146
	v_lshlrev_b64 v[148:149], 12, v[148:149]
	s_nop 0
	v_addc_co_u32_e32 v155, vcc, 0, v147, vcc
	v_lshl_add_u64 v[148:149], s[82:83], 0, v[148:149]
	s_mov_b64 s[20:21], -1
	s_and_b64 vcc, exec, s[4:5]
	v_lshl_add_u64 v[148:149], v[142:143], 1, v[148:149]
	s_waitcnt vmcnt(3)
	v_lshlrev_b32_e32 v159, 16, v172
	v_and_b32_e32 v158, 0xffff0000, v172
	v_lshlrev_b32_e32 v155, 16, v173
	v_and_b32_e32 v154, 0xffff0000, v173
	v_lshlrev_b32_e32 v160, 16, v174
	v_and_b32_e32 v157, 0xffff0000, v174
	v_lshlrev_b32_e32 v156, 16, v175
	v_and_b32_e32 v145, 0xffff0000, v175
	s_cbranch_vccnz .LBB0_895
	v_mul_f32_e32 v161, v46, v159
	v_mul_f32_e32 v162, v47, v158
	v_cvt_pk_bf16_f32 v166, v161, v162
	v_mul_f32_e32 v161, v48, v155
	v_mul_f32_e32 v162, v49, v154
	v_cvt_pk_bf16_f32 v167, v161, v162
	v_mul_f32_e32 v161, v42, v160
	v_mul_f32_e32 v162, v43, v157
	s_mov_b64 s[20:21], 0
	v_cvt_pk_bf16_f32 v168, v161, v162
	v_mul_f32_e32 v161, v44, v156
	v_mul_f32_e32 v162, v45, v145
	v_cvt_pk_bf16_f32 v169, v161, v162
	global_store_dwordx4 v[148:149], v[166:169], off
.LBB0_895:
	s_andn2_b64 vcc, exec, s[20:21]
	s_cbranch_vccnz .LBB0_897
	v_max_f32_e32 v159, v159, v159
	v_max_f32_e32 v160, v160, v160
	v_max_f32_e32 v158, v158, v158
	v_max_f32_e32 v157, v157, v157
	v_max_f32_e32 v155, v155, v155
	v_max_f32_e32 v156, v156, v156
	v_max_f32_e32 v154, v154, v154
	v_max_f32_e32 v145, v145, v145
	v_max_f32_e32 v159, 0xda24260, v159
	v_max_f32_e32 v160, 0xda24260, v160
	v_max_f32_e32 v158, 0xda24260, v158
	v_max_f32_e32 v157, 0xda24260, v157
	v_max_f32_e32 v161, 0xda24260, v155
	v_max_f32_e32 v162, 0xda24260, v156
	v_max_f32_e32 v163, 0xda24260, v154
	v_max_f32_e32 v145, 0xda24260, v145
	v_rcp_f32_e32 v154, v159
	v_rcp_f32_e32 v156, v160
	v_rcp_f32_e32 v155, v158
	v_rcp_f32_e32 v157, v157
	v_rcp_f32_e32 v158, v161
	v_rcp_f32_e32 v160, v162
	v_rcp_f32_e32 v159, v163
	v_rcp_f32_e32 v161, v145
	s_waitcnt vmcnt(2)
	v_lshlrev_b32_e32 v162, 16, v176
	v_and_b32_e32 v163, 0xffff0000, v176
	v_lshlrev_b32_e32 v170, 16, v178
	v_and_b32_e32 v171, 0xffff0000, v178
	v_lshlrev_b32_e32 v166, 16, v177
	v_and_b32_e32 v167, 0xffff0000, v177
	v_lshlrev_b32_e32 v168, 16, v179
	v_and_b32_e32 v169, 0xffff0000, v179
	v_pk_mul_f32 v[154:155], v[154:155], v[162:163]
	v_pk_mul_f32 v[156:157], v[156:157], v[170:171]
	v_pk_mul_f32 v[158:159], v[158:159], v[166:167]
	v_pk_mul_f32 v[160:161], v[160:161], v[168:169]
	v_pk_mul_f32 v[46:47], v[46:47], v[154:155]
	v_pk_mul_f32 v[42:43], v[42:43], v[156:157]
	v_pk_mul_f32 v[48:49], v[48:49], v[158:159]
	v_pk_mul_f32 v[44:45], v[44:45], v[160:161]
.LBB0_897:
	v_lshl_add_u64 v[154:155], v[146:147], 0, s[12:13]
	s_and_b64 vcc, exec, s[4:5]
	s_mov_b64 s[20:21], -1
	s_waitcnt vmcnt(1)
	v_lshlrev_b32_e32 v159, 16, v180
	v_and_b32_e32 v158, 0xffff0000, v180
	v_lshlrev_b32_e32 v155, 16, v181
	v_and_b32_e32 v154, 0xffff0000, v181
	v_lshlrev_b32_e32 v160, 16, v182
	v_and_b32_e32 v157, 0xffff0000, v182
	v_lshlrev_b32_e32 v156, 16, v183
	v_and_b32_e32 v145, 0xffff0000, v183
	s_cbranch_vccnz .LBB0_899
	v_mul_f32_e32 v161, v14, v159
	v_mul_f32_e32 v162, v15, v158
	v_cvt_pk_bf16_f32 v166, v161, v162
	v_mul_f32_e32 v161, v16, v155
	v_mul_f32_e32 v162, v17, v154
	v_cvt_pk_bf16_f32 v167, v161, v162
	v_mul_f32_e32 v161, v10, v160
	v_mul_f32_e32 v162, v11, v157
	s_mov_b64 s[20:21], 0
	v_cvt_pk_bf16_f32 v168, v161, v162
	v_mul_f32_e32 v161, v12, v156
	v_mul_f32_e32 v162, v13, v145
	v_cvt_pk_bf16_f32 v169, v161, v162
	global_store_dwordx4 v[148:149], v[166:169], off offset:256
.LBB0_899:
	s_andn2_b64 vcc, exec, s[20:21]
	s_cbranch_vccnz .LBB0_901
	v_max_f32_e32 v159, v159, v159
	v_max_f32_e32 v160, v160, v160
	v_max_f32_e32 v158, v158, v158
	v_max_f32_e32 v157, v157, v157
	v_max_f32_e32 v155, v155, v155
	v_max_f32_e32 v156, v156, v156
	v_max_f32_e32 v154, v154, v154
	v_max_f32_e32 v145, v145, v145
	v_max_f32_e32 v159, 0xda24260, v159
	v_max_f32_e32 v160, 0xda24260, v160
	v_max_f32_e32 v158, 0xda24260, v158
	v_max_f32_e32 v157, 0xda24260, v157
	v_max_f32_e32 v161, 0xda24260, v155
	v_max_f32_e32 v162, 0xda24260, v156
	v_max_f32_e32 v163, 0xda24260, v154
	v_max_f32_e32 v145, 0xda24260, v145
	v_rcp_f32_e32 v154, v159
	v_rcp_f32_e32 v156, v160
	v_rcp_f32_e32 v155, v158
	v_rcp_f32_e32 v157, v157
	v_rcp_f32_e32 v158, v161
	v_rcp_f32_e32 v160, v162
	v_rcp_f32_e32 v159, v163
	v_rcp_f32_e32 v161, v145
	s_waitcnt vmcnt(0)
	v_lshlrev_b32_e32 v162, 16, v184
	v_and_b32_e32 v163, 0xffff0000, v184
	v_lshlrev_b32_e32 v166, 16, v186
	v_and_b32_e32 v167, 0xffff0000, v186
	v_lshlrev_b32_e32 v146, 16, v185
	v_and_b32_e32 v147, 0xffff0000, v185
	v_lshlrev_b32_e32 v148, 16, v187
	v_and_b32_e32 v149, 0xffff0000, v187
	v_pk_mul_f32 v[154:155], v[154:155], v[162:163]
	v_pk_mul_f32 v[156:157], v[156:157], v[166:167]
	v_pk_mul_f32 v[146:147], v[158:159], v[146:147]
	v_pk_mul_f32 v[148:149], v[160:161], v[148:149]
	v_pk_mul_f32 v[14:15], v[14:15], v[154:155]
	v_pk_mul_f32 v[10:11], v[10:11], v[156:157]
	v_pk_mul_f32 v[16:17], v[16:17], v[146:147]
	v_pk_mul_f32 v[12:13], v[12:13], v[148:149]
